# kernel entry: three 4-byte scalar loads touch the remaining kernarg lines together with the first group (no three serial scalar-cache misses), stacked
# speedup vs baseline: 1.0031x; 1.0024x over previous
_Z6mk_fwd4Args:
	s_load_dwordx8 s[4:11], s[0:1], 0xc0
	s_load_dword s54, s[0:1], 0xf8
	s_load_dwordx4 s[68:71], s[0:1], 0xe0
	s_load_dwordx2 s[52:53], s[0:1], 0xf0
	s_load_dword s72, s[0:1], 0x0
	s_load_dword s73, s[0:1], 0x40
	s_load_dword s74, s[0:1], 0x80
	s_mov_b32 s56, s2
	v_readfirstlane_b32 s2, v0
	s_mov_b32 s33, s56
	s_waitcnt lgkmcnt(0)
	v_writelane_b32 v254, s4, 0
	s_nop 1
	v_writelane_b32 v254, s5, 1
	v_writelane_b32 v254, s6, 2
	v_writelane_b32 v254, s7, 3
	v_writelane_b32 v254, s8, 4
	v_writelane_b32 v254, s9, 5
	v_writelane_b32 v254, s10, 6
	v_writelane_b32 v254, s11, 7
	s_add_u32 s4, s0, 0xf8
	s_addc_u32 s5, s1, 0
	v_writelane_b32 v254, s4, 8
	s_and_b32 s3, s54, 7
	s_cmp_lg_u32 s3, 0
	v_writelane_b32 v254, s5, 9
	s_cbranch_scc0 .LBB0_101
	v_cmp_gt_u32_e64 s[6:7], 64, v0
	s_and_saveexec_b64 s[4:5], s[6:7]
